# attention loop: two query sets' row-max chains interleaved, pads after permlane swaps dropped
# speedup vs baseline: 1.0016x; 1.0016x over previous
; __device__ __forceinline__ void attn_block(const Params& P, int bh, int qb, unsigned char* smem) {
;     ...
;         for (int u = 0; u < 2; ++u) {
;             float mx = -INFINITY;
; #pragma unroll
;             for (int c = 0; c < 4; ++c) {
;                 sa[u][c] -= ck[c];
;                 mx = fmaxf(mx, fmaxf(fmaxf(sa[u][c][0], sa[u][c][1]), fmaxf(sa[u][c][2], sa[u][c][3])));
;             }
;             mx = x4_max(mx);
;             if (__builtin_amdgcn_ballot_w64(mx > m[u]) != 0ull) {
;                 const float mn = fmaxf(m[u], mx);
;                 const float alpha = __builtin_amdgcn_exp2f(m[u] - mn);
;                 m[u] = mn;
; #pragma unroll
;                 for (int c = 0; c < 5; ++c) o[u][c] *= alpha;
;             }
.LBB0_717:
	s_nop 1
	v_max3_f32 v192, v102, v103, v104
	v_max3_f32 v193, v105, v98, v99
	v_max3_f32 v194, v100, v101, v110
	v_max3_f32 v195, v111, v112, v113
	v_max3_f32 v128, v106, v107, v108
	v_max3_f32 v192, v192, v193, v109
	v_max3_f32 v194, v194, v195, v128
	v_max_f32_e32 v192, v192, v194
	v_max3_f32 v194, v86, v87, v88
	v_max3_f32 v195, v89, v82, v83
	v_max3_f32 v128, v84, v85, v94
	v_max3_f32 v129, v95, v96, v97
	v_max3_f32 v4, v90, v91, v92
	v_max3_f32 v194, v194, v195, v93
	v_max3_f32 v128, v128, v129, v4
	v_mov_b32_e32 v193, v192
	v_max_f32_e32 v194, v194, v128
	v_mov_b32_e32 v195, v194
	v_permlane32_swap_b32_e32 v192, v193
	s_nop 0
	v_permlane32_swap_b32_e32 v194, v195
	v_max_f32_e32 v192, v192, v193
	v_max_f32_e32 v194, v194, v195
	v_mov_b32_e32 v193, v192
	v_mov_b32_e32 v195, v194
	s_nop 0
	v_permlane16_swap_b32_e32 v192, v193
	v_permlane16_swap_b32_e32 v194, v195
	v_max_f32_e32 v192, v192, v193
	v_max_f32_e32 v194, v194, v195
	v_cmp_gt_f32_e32 vcc, v192, v187
	s_cbranch_vccz .LBB0_719
	v_max_f32_e32 v193, v187, v192
	v_sub_f32_e32 v192, v187, v193
	v_exp_f32_e32 v192, v192
	v_mov_b32_e32 v187, v193
	v_xor_b32_e32 v196, 0x80000000, v193
	v_pk_mul_f32 v[68:69], v[68:69], v[192:193] op_sel_hi:[1,0]
	v_pk_mul_f32 v[66:67], v[66:67], v[192:193] op_sel_hi:[1,0]
	v_pk_mul_f32 v[52:53], v[52:53], v[192:193] op_sel_hi:[1,0]
	v_pk_mul_f32 v[50:51], v[50:51], v[192:193] op_sel_hi:[1,0]
	v_pk_mul_f32 v[48:49], v[48:49], v[192:193] op_sel_hi:[1,0]
	v_pk_mul_f32 v[46:47], v[46:47], v[192:193] op_sel_hi:[1,0]
	v_pk_mul_f32 v[44:45], v[44:45], v[192:193] op_sel_hi:[1,0]
	v_pk_mul_f32 v[42:43], v[42:43], v[192:193] op_sel_hi:[1,0]
	v_pk_mul_f32 v[80:81], v[80:81], v[192:193] op_sel_hi:[1,0]
	v_pk_mul_f32 v[78:79], v[78:79], v[192:193] op_sel_hi:[1,0]
.LBB0_719:
	v_cmp_gt_f32_e32 vcc, v194, v2
	s_cbranch_vccz .LBB0_708
	v_max_f32_e32 v193, v2, v194
	v_sub_f32_e32 v192, v2, v193
	v_exp_f32_e32 v192, v192
	v_mov_b32_e32 v2, v193
	v_xor_b32_e32 v230, 0x80000000, v193
	v_pk_mul_f32 v[36:37], v[36:37], v[192:193] op_sel_hi:[1,0]
	v_pk_mul_f32 v[34:35], v[34:35], v[192:193] op_sel_hi:[1,0]
	v_pk_mul_f32 v[32:33], v[32:33], v[192:193] op_sel_hi:[1,0]
	v_pk_mul_f32 v[30:31], v[30:31], v[192:193] op_sel_hi:[1,0]
	v_pk_mul_f32 v[28:29], v[28:29], v[192:193] op_sel_hi:[1,0]
	v_pk_mul_f32 v[26:27], v[26:27], v[192:193] op_sel_hi:[1,0]
	v_pk_mul_f32 v[24:25], v[24:25], v[192:193] op_sel_hi:[1,0]
	v_pk_mul_f32 v[22:23], v[22:23], v[192:193] op_sel_hi:[1,0]
	v_pk_mul_f32 v[40:41], v[40:41], v[192:193] op_sel_hi:[1,0]
	v_pk_mul_f32 v[38:39], v[38:39], v[192:193] op_sel_hi:[1,0]
	s_branch .LBB0_708
